# v025 + ret_out score loop: the 8 K-fragment loads of each 32x32 score tile issued together with counted waits instead of load/wait/MFMA one at a time
# speedup vs baseline: 1.0119x; 1.0033x over previous
; #define LAS __attribute__((address_space(3)))
; __device__ __forceinline__ unsigned cvt_pk_bf16(float lo, float hi) { f32x2 v = {lo, hi}; bf16v2_t r = __builtin_convertvector(v, bf16v2_t); return __builtin_bit_cast(unsigned, r); }
; #define MFMA32(a, b, c) __builtin_amdgcn_mfma_f32_32x32x16_bf16((a), (b), (c), 0, 0, 0)
; __device__ __forceinline__ void phase_ret_out(const Frame& F, const Args& a, int l) {
;     ...
;         for (int k2 = 0; k2 < 2; ++k2) {
;             const int kt = 2 * dj + k2;
;             const bf16* krow_ = RKm + ((size_t)(((tok0 + 32 * kt) >> 5) * 4 + h) * 8) * 512 + lane * 8;
;             f32x16 x;
; #pragma unroll
;             for (int e = 0; e < 16; ++e) x[e] = 0.f;
; #pragma unroll
;             for (int ks = 0; ks < 8; ++ks) { const bf16x8 kf = *(const bf16x8*)(krow_ + 512 * ks); x = MFMA32(kf, qf[ks], x); }
; #pragma unroll
;             for (int q4 = 0; q4 < 4; ++q4) {
;                 float pv[4];
; #pragma unroll
;                 for (int e = 0; e < 4; ++e) { const int jp = 32 * kt + e + 8 * q4 + 4 * hh; const int df = ip - jp;
;                     const float f0 = (df >= 0) ? __builtin_amdgcn_exp2f(l2g0 * (float)df) : 0.f, f1 = (df <= 0) ? __builtin_amdgcn_exp2f(l2g1 * (float)(-df)) : 0.f;
;                     pv[e] = x[4 * q4 + e] * (f0 + f1); }
;                 v2u pw; pw.x = cvt_pk_bf16(pv[0], pv[1]); pw.y = cvt_pk_bf16(pv[2], pv[3]);
;                 *(LAS v2u*)(Pl + (qi * 32 + li) * PLD + (kt * 32 + 8 * q4 + 4 * hh) * 2) = pw;
.LBB0_1207:
	s_or_b32 s8, s8, s34
	v_cndmask_b32_e64 v0, 0, 1, s[6:7]
	s_ashr_i32 s7, s8, 31
	s_add_u32 s6, s26, s8
	s_addc_u32 s7, s27, s7
	s_lshl_b64 s[6:7], s[6:7], 10
	v_lshl_add_u64 v[22:23], v[16:17], 0, s[6:7]
	v_cmp_ne_u32_e32 vcc, 1, v0
	global_load_dwordx4 v[24:27], v[22:23], off
	global_load_dwordx4 v[28:31], v[22:23], off offset:1024
	global_load_dwordx4 v[32:35], v[22:23], off offset:2048
	global_load_dwordx4 v[36:39], v[22:23], off offset:3072
	v_add_co_u32_e64 v22, s[6:7], s33, v22
	s_nop 1
	v_addc_co_u32_e64 v23, s[6:7], 0, v23, s[6:7]
	global_load_dwordx4 v[40:43], v[22:23], off
	global_load_dwordx4 v[48:51], v[22:23], off offset:1024
	global_load_dwordx4 v[52:55], v[22:23], off offset:2048
	global_load_dwordx4 v[56:59], v[22:23], off offset:3072
	s_and_b64 vcc, exec, vcc
	s_nop 0
	v_lshl_add_u32 v23, s8, 1, v113
	s_waitcnt vmcnt(7)
	v_mfma_f32_32x32x16_bf16 v[0:15], v[24:27], v[92:95], 0
	s_waitcnt vmcnt(6)
	v_mfma_f32_32x32x16_bf16 v[0:15], v[28:31], v[88:91], v[0:15]
	s_waitcnt vmcnt(5)
	v_mfma_f32_32x32x16_bf16 v[0:15], v[32:35], v[84:87], v[0:15]
	s_waitcnt vmcnt(4)
	v_mfma_f32_32x32x16_bf16 v[0:15], v[36:39], v[80:83], v[0:15]
	s_waitcnt vmcnt(3)
	v_mfma_f32_32x32x16_bf16 v[0:15], v[40:43], v[76:79], v[0:15]
	s_waitcnt vmcnt(2)
	v_mfma_f32_32x32x16_bf16 v[0:15], v[48:51], v[72:75], v[0:15]
	s_waitcnt vmcnt(1)
	v_mfma_f32_32x32x16_bf16 v[0:15], v[52:55], v[68:71], v[0:15]
	s_waitcnt vmcnt(0)
	v_mfma_f32_32x32x16_bf16 v[0:15], v[56:59], v[64:67], v[0:15]
	v_or_b32_e32 v18, s8, v119
	v_sub_u32_e32 v22, v111, v18
	v_sub_u32_e32 v19, 0, v22
	v_cvt_f32_u32_e32 v19, v19
	v_cvt_f32_u32_e32 v18, v22
	v_sub_u32_e32 v21, 1, v22
	v_cvt_f32_u32_e32 v21, v21
	v_mul_f32_e64 v19, -v45, v19
	v_exp_f32_e32 v20, v19
	v_add_u32_e32 v19, -1, v22
	v_cvt_f32_u32_e32 v19, v19
	v_mul_f32_e64 v18, -v44, v18
	v_exp_f32_e32 v18, v18
	v_mul_f32_e64 v21, -v45, v21
	v_mul_f32_e64 v19, -v44, v19
	v_exp_f32_e32 v19, v19
	v_exp_f32_e32 v21, v21
	v_cmp_lt_i32_e64 s[6:7], 0, v22
	v_cmp_lt_i32_e64 s[8:9], -1, v22
	s_nop 0
	v_cndmask_b32_e64 v19, 0, v19, s[6:7]
	v_cndmask_b32_e64 v18, 0, v18, s[8:9]
	v_cmp_gt_i32_e64 s[6:7], 1, v22
	v_cmp_gt_i32_e64 s[8:9], 2, v22
	s_nop 0
	v_cndmask_b32_e64 v20, 0, v20, s[6:7]
	v_cndmask_b32_e64 v21, 0, v21, s[8:9]
	v_pk_add_f32 v[18:19], v[18:19], v[20:21]
	v_sub_u32_e32 v21, 3, v22
	v_pk_mul_f32 v[0:1], v[18:19], v[0:1]
	v_sub_u32_e32 v19, 2, v22
	v_cvt_f32_u32_e32 v19, v19
	v_add_u32_e32 v18, -2, v22
	v_cvt_f32_u32_e32 v18, v18
	v_cvt_f32_u32_e32 v21, v21
	v_mul_f32_e64 v19, -v45, v19
	v_exp_f32_e32 v20, v19
	v_add_u32_e32 v19, -3, v22
	v_cvt_f32_u32_e32 v19, v19
	v_mul_f32_e64 v18, -v44, v18
	v_exp_f32_e32 v18, v18
	v_mul_f32_e64 v21, -v45, v21
	v_mul_f32_e64 v19, -v44, v19
	v_exp_f32_e32 v19, v19
	v_exp_f32_e32 v21, v21
	v_cmp_lt_i32_e64 s[6:7], 1, v22
	v_cmp_lt_i32_e64 s[8:9], 2, v22
	v_cvt_pk_bf16_f32 v0, v0, v1
	v_cndmask_b32_e64 v18, 0, v18, s[6:7]
	v_cndmask_b32_e64 v19, 0, v19, s[8:9]
	v_cmp_gt_i32_e64 s[6:7], 3, v22
	v_cmp_gt_i32_e64 s[8:9], 4, v22
	s_nop 0
	v_cndmask_b32_e64 v20, 0, v20, s[6:7]
	v_cndmask_b32_e64 v21, 0, v21, s[8:9]
	v_pk_add_f32 v[18:19], v[18:19], v[20:21]
	v_cmp_lt_i32_e64 s[6:7], 7, v22
	v_pk_mul_f32 v[2:3], v[18:19], v[2:3]
	v_sub_u32_e32 v19, 9, v22
	v_cvt_pk_bf16_f32 v1, v2, v3
	v_sub_u32_e32 v3, 8, v22
	v_cvt_f32_u32_e32 v3, v3
	v_add_u32_e32 v2, -8, v22
	v_cvt_f32_u32_e32 v2, v2
	v_cvt_f32_u32_e32 v19, v19
	v_mul_f32_e64 v3, -v45, v3
	v_exp_f32_e32 v18, v3
	v_add_u32_e32 v3, -9, v22
	v_cvt_f32_u32_e32 v3, v3
	v_mul_f32_e64 v2, -v44, v2
	v_exp_f32_e32 v2, v2
	v_mul_f32_e64 v19, -v45, v19
	v_mul_f32_e64 v3, -v44, v3
	v_exp_f32_e32 v3, v3
	v_exp_f32_e32 v19, v19
	v_cmp_lt_i32_e64 s[8:9], 8, v22
	v_cndmask_b32_e64 v2, 0, v2, s[6:7]
	v_cmp_gt_i32_e64 s[6:7], 9, v22
	v_cndmask_b32_e64 v3, 0, v3, s[8:9]
	v_cmp_gt_i32_e64 s[8:9], 10, v22
	v_cndmask_b32_e64 v18, 0, v18, s[6:7]
	v_cmp_lt_i32_e64 s[6:7], 9, v22
	v_cndmask_b32_e64 v19, 0, v19, s[8:9]
	v_pk_add_f32 v[2:3], v[2:3], v[18:19]
	v_sub_u32_e32 v19, 11, v22
	v_pk_mul_f32 v[2:3], v[2:3], v[4:5]
	v_sub_u32_e32 v5, 10, v22
	v_cvt_f32_u32_e32 v5, v5
	v_add_u32_e32 v4, -10, v22
	v_cvt_f32_u32_e32 v4, v4
	v_cvt_f32_u32_e32 v19, v19
	v_mul_f32_e64 v5, -v45, v5
	v_exp_f32_e32 v18, v5
	v_add_u32_e32 v5, -11, v22
	v_cvt_f32_u32_e32 v5, v5
	v_mul_f32_e64 v4, -v44, v4
	v_exp_f32_e32 v4, v4
	v_mul_f32_e64 v19, -v45, v19
	v_mul_f32_e64 v5, -v44, v5
	v_exp_f32_e32 v5, v5
	v_exp_f32_e32 v19, v19
	v_cmp_lt_i32_e64 s[8:9], 10, v22
	v_cndmask_b32_e64 v4, 0, v4, s[6:7]
	v_cmp_gt_i32_e64 s[6:7], 11, v22
	v_cndmask_b32_e64 v5, 0, v5, s[8:9]
	v_cmp_gt_i32_e64 s[8:9], 12, v22
	v_cndmask_b32_e64 v18, 0, v18, s[6:7]
	v_cvt_pk_bf16_f32 v2, v2, v3
	v_cndmask_b32_e64 v19, 0, v19, s[8:9]
	v_pk_add_f32 v[4:5], v[4:5], v[18:19]
	v_cmp_lt_i32_e64 s[6:7], 15, v22
	v_pk_mul_f32 v[4:5], v[4:5], v[6:7]
	v_cmp_lt_i32_e64 s[8:9], 16, v22
	v_cvt_pk_bf16_f32 v3, v4, v5
	ds_write2_b64 v23, v[0:1], v[2:3] offset1:2
	v_sub_u32_e32 v1, 16, v22
	v_cvt_f32_u32_e32 v1, v1
	v_add_u32_e32 v0, -16, v22
	v_cvt_f32_u32_e32 v0, v0
	v_sub_u32_e32 v3, 17, v22
	v_mul_f32_e64 v1, -v45, v1
	v_exp_f32_e32 v2, v1
	v_subrev_u32_e32 v1, 17, v22
	v_cvt_f32_u32_e32 v1, v1
	v_cvt_f32_u32_e32 v3, v3
	v_mul_f32_e64 v0, -v44, v0
	v_exp_f32_e32 v0, v0
	v_mul_f32_e64 v1, -v44, v1
	v_exp_f32_e32 v1, v1
	v_mul_f32_e64 v3, -v45, v3
	v_exp_f32_e32 v3, v3
	v_cndmask_b32_e64 v0, 0, v0, s[6:7]
	v_cndmask_b32_e64 v1, 0, v1, s[8:9]
	v_cmp_gt_i32_e64 s[6:7], 17, v22
	v_cmp_gt_i32_e64 s[8:9], 18, v22
	v_sub_u32_e32 v5, 19, v22
	v_cndmask_b32_e64 v2, 0, v2, s[6:7]
	v_cndmask_b32_e64 v3, 0, v3, s[8:9]
; #define LAS __attribute__((address_space(3)))
; #define LDS_WAIT() asm volatile("s_waitcnt lgkmcnt(0)" ::: "memory")
; __device__ __forceinline__ unsigned cvt_pk_bf16(float lo, float hi) { f32x2 v = {lo, hi}; bf16v2_t r = __builtin_convertvector(v, bf16v2_t); return __builtin_bit_cast(unsigned, r); }
; __device__ __forceinline__ void phase_ret_out(const Frame& F, const Args& a, int l) {
;     ...
;             for (int q4 = 0; q4 < 4; ++q4) {
;                 float pv[4];
; #pragma unroll
;                 for (int e = 0; e < 4; ++e) { const int jp = 32 * kt + e + 8 * q4 + 4 * hh; const int df = ip - jp;
;                     const float f0 = (df >= 0) ? __builtin_amdgcn_exp2f(l2g0 * (float)df) : 0.f, f1 = (df <= 0) ? __builtin_amdgcn_exp2f(l2g1 * (float)(-df)) : 0.f;
;                     pv[e] = x[4 * q4 + e] * (f0 + f1); }
;                 v2u pw; pw.x = cvt_pk_bf16(pv[0], pv[1]); pw.y = cvt_pk_bf16(pv[2], pv[3]);
;                 *(LAS v2u*)(Pl + (qi * 32 + li) * PLD + (kt * 32 + 8 * q4 + 4 * hh) * 2) = pw;
;             }
;         }
;         LDS_WAIT(); __syncthreads();
;         const float e0 = l2g0 * (float)(ip + 1), e1 = l2g1 * (float)(128 - ip);
;         const float ratio = __builtin_amdgcn_exp2f(e0 - e1), xi1 = __builtin_amdgcn_exp2f(e1);
;         f32x16 o[4]; float s1 = 0.f, s2 = 0.f;
; #pragma unroll
;         for (int dt = 0; dt < 4; ++dt) {
;             const int dvr = 128 * dj + 32 * dt + li;
;             const bf16* srow = SB + (((size_t)((seq * 4 + h) * 32 + n) * 8 + 4 * dj + dt) * 2) * 8 * 512 + lane * 8;
;             const bf16* vrow = RVT + ((size_t)(h * 8 + 4 * dj + dt) * (T / 16) + (tok0 >> 4)) * 512 + lane * 8;
;             f32x16 acc;
; #pragma unroll
;             for (int e = 0; e < 16; ++e) acc[e] = 0.f;
;             bf16x8 s0f[8], s1f[8], vff[8];
; #pragma unroll
;             for (int ks = 0; ks < 8; ++ks) { s0f[ks] = *(const bf16x8*)(srow + 512 * ks); s1f[ks] = *(const bf16x8*)(srow + 4096 + 512 * ks); vff[ks] = *(const bf16x8*)(vrow + 512 * ks); }
	v_pk_add_f32 v[0:1], v[0:1], v[2:3]
	v_sub_u32_e32 v3, 18, v22
	v_cvt_f32_u32_e32 v3, v3
	v_subrev_u32_e32 v2, 18, v22
	v_cvt_f32_u32_e32 v2, v2
	v_cvt_f32_u32_e32 v5, v5
	v_mul_f32_e64 v3, -v45, v3
	v_exp_f32_e32 v4, v3
	v_subrev_u32_e32 v3, 19, v22
	v_cvt_f32_u32_e32 v3, v3
	v_mul_f32_e64 v2, -v44, v2
	v_exp_f32_e32 v2, v2
	v_mul_f32_e64 v5, -v45, v5
	v_mul_f32_e64 v3, -v44, v3
	v_exp_f32_e32 v3, v3
	v_exp_f32_e32 v5, v5
	v_cmp_lt_i32_e64 s[6:7], 17, v22
	v_cmp_lt_i32_e64 s[8:9], 18, v22
	v_pk_mul_f32 v[0:1], v[0:1], v[8:9]
	v_cndmask_b32_e64 v2, 0, v2, s[6:7]
	v_cndmask_b32_e64 v3, 0, v3, s[8:9]
	v_cmp_gt_i32_e64 s[6:7], 19, v22
	v_cmp_gt_i32_e64 s[8:9], 20, v22
	v_cvt_pk_bf16_f32 v0, v0, v1
	v_cndmask_b32_e64 v4, 0, v4, s[6:7]
	v_cndmask_b32_e64 v5, 0, v5, s[8:9]
	v_pk_add_f32 v[2:3], v[2:3], v[4:5]
	v_sub_u32_e32 v5, 25, v22
	v_pk_mul_f32 v[2:3], v[2:3], v[10:11]
	v_cvt_f32_u32_e32 v5, v5
	v_cvt_pk_bf16_f32 v1, v2, v3
	v_sub_u32_e32 v3, 24, v22
	v_cvt_f32_u32_e32 v3, v3
	v_subrev_u32_e32 v2, 24, v22
	v_cvt_f32_u32_e32 v2, v2
	v_mul_f32_e64 v5, -v45, v5
	v_mul_f32_e64 v3, -v45, v3
	v_exp_f32_e32 v4, v3
	v_subrev_u32_e32 v3, 25, v22
	v_cvt_f32_u32_e32 v3, v3
	v_mul_f32_e64 v2, -v44, v2
	v_exp_f32_e32 v2, v2
	v_exp_f32_e32 v5, v5
	v_mul_f32_e64 v3, -v44, v3
	v_exp_f32_e32 v3, v3
	v_cmp_lt_i32_e64 s[6:7], 23, v22
	v_cmp_lt_i32_e64 s[8:9], 24, v22
	v_sub_u32_e32 v7, 27, v22
	v_cndmask_b32_e64 v2, 0, v2, s[6:7]
	v_cndmask_b32_e64 v3, 0, v3, s[8:9]
	v_cmp_gt_i32_e64 s[6:7], 25, v22
	v_cmp_gt_i32_e64 s[8:9], 26, v22
	v_cvt_f32_u32_e32 v7, v7
	v_cndmask_b32_e64 v4, 0, v4, s[6:7]
	v_cndmask_b32_e64 v5, 0, v5, s[8:9]
	v_pk_add_f32 v[2:3], v[2:3], v[4:5]
	v_sub_u32_e32 v5, 26, v22
	v_cvt_f32_u32_e32 v5, v5
	v_subrev_u32_e32 v4, 26, v22
	v_cvt_f32_u32_e32 v4, v4
	v_mul_f32_e64 v7, -v45, v7
	v_mul_f32_e64 v5, -v45, v5
	v_exp_f32_e32 v6, v5
	v_subrev_u32_e32 v5, 27, v22
	v_cvt_f32_u32_e32 v5, v5
	v_mul_f32_e64 v4, -v44, v4
	v_exp_f32_e32 v4, v4
	v_exp_f32_e32 v7, v7
	v_mul_f32_e64 v5, -v44, v5
	v_exp_f32_e32 v5, v5
	v_cmp_lt_i32_e64 s[6:7], 25, v22
	v_cmp_lt_i32_e64 s[8:9], 26, v22
	v_pk_mul_f32 v[2:3], v[2:3], v[12:13]
	v_cndmask_b32_e64 v4, 0, v4, s[6:7]
	v_cndmask_b32_e64 v5, 0, v5, s[8:9]
	v_cmp_gt_i32_e64 s[6:7], 27, v22
	v_cmp_gt_i32_e64 s[8:9], 28, v22
	v_cvt_pk_bf16_f32 v2, v2, v3
	v_cndmask_b32_e64 v6, 0, v6, s[6:7]
	v_cndmask_b32_e64 v7, 0, v7, s[8:9]
	v_pk_add_f32 v[4:5], v[4:5], v[6:7]
	s_mov_b32 s8, 32
	v_pk_mul_f32 v[4:5], v[4:5], v[14:15]
	s_mov_b64 s[6:7], 0
	v_cvt_pk_bf16_f32 v3, v4, v5
	ds_write2_b64 v23, v[0:1], v[2:3] offset0:4 offset1:6
	s_cbranch_vccz .LBB0_1207
	s_and_b32 s6, s29, 0xffffff80
	s_lshl_b32 s7, s23, 5
	s_or_b32 s6, s7, s6
	s_or_b32 s6, s6, s35
	s_ashr_i32 s7, s6, 31
	s_lshl_b64 s[6:7], s[6:7], 17
	v_lshl_add_u64 v[56:57], v[126:127], 0, s[6:7]
	s_waitcnt lgkmcnt(0)
	s_waitcnt lgkmcnt(0)
	s_barrier
	global_load_dwordx4 v[0:3], v[56:57], off
	global_load_dwordx4 v[40:43], v[56:57], off offset:1024
	global_load_dwordx4 v[36:39], v[56:57], off offset:2048
	global_load_dwordx4 v[32:35], v[56:57], off offset:3072
	s_lshr_b64 s[6:7], s[26:27], 4
	s_movk_i32 s27, 0x2000
	v_add_co_u32_e32 v8, vcc, s27, v56
	s_lshl_b32 s8, s23, 3
	s_nop 0
	v_addc_co_u32_e32 v9, vcc, 0, v57, vcc
	s_movk_i32 s27, 0x3000
	s_add_i32 s26, s8, s22
	v_add_co_u32_e32 v4, vcc, s27, v56
	s_mul_i32 s8, s26, 0xa00
	s_nop 0
	v_addc_co_u32_e32 v5, vcc, 0, v57, vcc
	s_mul_hi_i32 s9, s26, 0xa00
	s_add_u32 s8, s8, s6
	v_add_co_u32_e32 v6, vcc, s33, v56
	s_addc_u32 s9, s9, s7
	s_nop 0
	v_addc_co_u32_e32 v7, vcc, 0, v57, vcc
	s_movk_i32 s27, 0x5000
	v_add_co_u32_e32 v54, vcc, s27, v56
	s_lshl_b64 s[8:9], s[8:9], 10
	s_nop 0
	v_addc_co_u32_e32 v55, vcc, 0, v57, vcc
	global_load_dwordx4 v[46:49], v[8:9], off offset:1024
	global_load_dwordx4 v[50:53], v[8:9], off offset:2048
	global_load_dwordx4 v[58:61], v[8:9], off offset:3072
	global_load_dwordx4 v[96:99], v[6:7], off
	global_load_dwordx4 v[100:103], v[4:5], off
	global_load_dwordx4 v[132:135], v[4:5], off offset:1024
	global_load_dwordx4 v[136:139], v[6:7], off offset:1024
	global_load_dwordx4 v[140:143], v[6:7], off offset:2048
	global_load_dwordx4 v[144:147], v[4:5], off offset:2048
	global_load_dwordx4 v[148:151], v[4:5], off offset:3072
	v_lshl_add_u64 v[8:9], v[108:109], 0, s[8:9]
	global_load_dwordx4 v[152:155], v[8:9], off
	global_load_dwordx4 v[156:159], v[8:9], off offset:1024
	global_load_dwordx4 v[160:163], v[8:9], off offset:2048
	global_load_dwordx4 v[164:167], v[8:9], off offset:3072
	v_add_co_u32_e32 v8, vcc, s33, v8
	s_movk_i32 s8, 0x4000
	s_nop 0
	v_addc_co_u32_e32 v9, vcc, 0, v9, vcc
	global_load_dwordx4 v[168:171], v[8:9], off offset:1024
	global_load_dwordx4 v[172:175], v[8:9], off offset:2048
	global_load_dwordx4 v[176:179], v[8:9], off
	global_load_dwordx4 v[180:183], v[6:7], off offset:3072
	global_load_dwordx4 v[188:191], v[4:5], off offset:-4096
	global_load_dwordx4 v[192:195], v[8:9], off offset:3072
	global_load_dwordx4 v[16:19], v[54:55], off offset:-4096
	global_load_dwordx4 v[196:199], v[54:55], off
	v_add_co_u32_e32 v62, vcc, s8, v56
	s_movk_i32 s8, 0x6000
	s_nop 0
	v_addc_co_u32_e32 v63, vcc, 0, v57, vcc
	global_load_dwordx4 v[200:203], v[62:63], off offset:1024
	v_pk_mul_f32 v[44:45], v[106:107], v[44:45] neg_lo:[0,1] neg_hi:[0,1]
	s_waitcnt vmcnt(26)
	v_mfma_f32_32x32x16_bf16 v[0:15], v[0:3], v[92:95], 0
	v_sub_f32_e32 v44, v44, v45
	v_exp_f32_e32 v130, v44
	v_exp_f32_e32 v128, v45
	s_waitcnt vmcnt(25)
	v_mfma_f32_32x32x16_bf16 v[0:15], v[40:43], v[88:91], v[0:15]
	global_load_dwordx4 v[40:43], v[62:63], off offset:2048
	s_waitcnt vmcnt(25)
; #define LAS __attribute__((address_space(3)))
; #define MFMA32(a, b, c) __builtin_amdgcn_mfma_f32_32x32x16_bf16((a), (b), (c), 0, 0, 0)
; __device__ __forceinline__ void phase_ret_out(const Frame& F, const Args& a, int l) {
;     ...
;         for (int dt = 0; dt < 4; ++dt) {
;             const int dvr = 128 * dj + 32 * dt + li;
;             const bf16* srow = SB + (((size_t)((seq * 4 + h) * 32 + n) * 8 + 4 * dj + dt) * 2) * 8 * 512 + lane * 8;
;             const bf16* vrow = RVT + ((size_t)(h * 8 + 4 * dj + dt) * (T / 16) + (tok0 >> 4)) * 512 + lane * 8;
;             f32x16 acc;
; #pragma unroll
;             for (int e = 0; e < 16; ++e) acc[e] = 0.f;
;             bf16x8 s0f[8], s1f[8], vff[8];
; #pragma unroll
;             for (int ks = 0; ks < 8; ++ks) { s0f[ks] = *(const bf16x8*)(srow + 512 * ks); s1f[ks] = *(const bf16x8*)(srow + 4096 + 512 * ks); vff[ks] = *(const bf16x8*)(vrow + 512 * ks); }
;             asm volatile("" ::: "memory");
; #pragma unroll
;             for (int ks = 0; ks < 8; ++ks) acc = MFMA32(s0f[ks], qf[ks], acc);
; #pragma unroll
;             for (int e = 0; e < 16; ++e) acc[e] *= ratio;
; #pragma unroll
;             for (int ks = 0; ks < 8; ++ks) acc = MFMA32(s1f[ks], qf[ks], acc);
; #pragma unroll
;             for (int e = 0; e < 16; ++e) acc[e] *= xi1;
; #pragma unroll
;             for (int ks = 0; ks < 8; ++ks) { const bf16x8 pf = *(const LAS bf16x8*)(Pl + (qi * 32 + li) * PLD + (16 * ks + 8 * hh) * 2); acc = MFMA32(vff[ks], pf, acc); }
; #pragma unroll
;             for (int e = 0; e < 16; ++e) { s1 += acc[e]; s2 += acc[e] * acc[e]; }
	v_mfma_f32_32x32x16_bf16 v[0:15], v[36:39], v[84:87], v[0:15]
	s_waitcnt vmcnt(24)
	v_mfma_f32_32x32x16_bf16 v[0:15], v[32:35], v[80:83], v[0:15]
	global_load_dwordx4 v[32:35], v[62:63], off offset:3072
	v_add_co_u32_e32 v62, vcc, s8, v56
	s_movk_i32 s8, 0x7000
	s_nop 0
	v_addc_co_u32_e32 v63, vcc, 0, v57, vcc
	global_load_dwordx4 v[36:39], v[62:63], off offset:1024
	s_waitcnt vmcnt(5)
	v_mfma_f32_32x32x16_bf16 v[16:31], v[16:19], v[92:95], 0
	s_waitcnt vmcnt(3)
	v_mfma_f32_32x32x16_bf16 v[16:31], v[200:203], v[88:91], v[16:31]
	v_mfma_f32_32x32x16_bf16 v[0:15], v[96:99], v[76:79], v[0:15]
	v_add_co_u32_e32 v96, vcc, s8, v56
	s_or_b32 s8, s26, 1
	s_nop 0
	v_addc_co_u32_e32 v97, vcc, 0, v57, vcc
	s_mul_hi_i32 s9, s8, 0xa00
	s_mulk_i32 s8, 0xa00
	v_mfma_f32_32x32x16_bf16 v[0:15], v[136:139], v[72:75], v[0:15]
	s_add_u32 s8, s8, s6
	s_addc_u32 s9, s9, s7
	s_lshl_b64 s[8:9], s[8:9], 10
	v_mfma_f32_32x32x16_bf16 v[0:15], v[140:143], v[68:71], v[0:15]
	v_mfma_f32_32x32x16_bf16 v[0:15], v[180:183], v[64:67], v[0:15]
	s_waitcnt vmcnt(2)
	v_mfma_f32_32x32x16_bf16 v[16:31], v[40:43], v[84:87], v[16:31]
	s_nop 9
	v_mul_f32_e64 v14, v130, v14
	v_mul_f32_e64 v15, v130, v15
	v_mul_f32_e64 v12, v130, v12
	v_mul_f32_e64 v13, v130, v13
	v_mul_f32_e64 v10, v130, v10
	v_mul_f32_e64 v11, v130, v11
	v_pk_mul_f32 v[8:9], v[130:131], v[8:9] op_sel_hi:[0,1]
	v_pk_mul_f32 v[6:7], v[130:131], v[6:7] op_sel_hi:[0,1]
	v_pk_mul_f32 v[4:5], v[130:131], v[4:5] op_sel_hi:[0,1]
	v_pk_mul_f32 v[2:3], v[130:131], v[2:3] op_sel_hi:[0,1]
	v_pk_mul_f32 v[0:1], v[130:131], v[0:1] op_sel_hi:[0,1]
	s_waitcnt vmcnt(1)
	v_mfma_f32_32x32x16_bf16 v[16:31], v[32:35], v[80:83], v[16:31]
	global_load_dwordx4 v[32:35], v[54:55], off offset:1024
	global_load_dwordx4 v[40:43], v[54:55], off offset:2048
	v_mfma_f32_32x32x16_bf16 v[16:31], v[196:199], v[76:79], v[16:31]
	v_mfma_f32_32x32x16_bf16 v[0:15], v[188:191], v[92:95], v[0:15]
	v_mfma_f32_32x32x16_bf16 v[0:15], v[46:49], v[88:91], v[0:15]
	v_mfma_f32_32x32x16_bf16 v[0:15], v[50:53], v[84:87], v[0:15]
	v_mfma_f32_32x32x16_bf16 v[0:15], v[58:61], v[80:83], v[0:15]
	v_mfma_f32_32x32x16_bf16 v[0:15], v[100:103], v[76:79], v[0:15]
	v_mfma_f32_32x32x16_bf16 v[0:15], v[132:135], v[72:75], v[0:15]
	v_mfma_f32_32x32x16_bf16 v[0:15], v[144:147], v[68:71], v[0:15]
	v_mfma_f32_32x32x16_bf16 v[0:15], v[148:151], v[64:67], v[0:15]
	s_waitcnt vmcnt(1)
	v_mfma_f32_32x32x16_bf16 v[16:31], v[32:35], v[72:75], v[16:31]
	global_load_dwordx4 v[32:35], v[54:55], off offset:3072
	s_nop 8
	v_mul_f32_e64 v14, v128, v14
	v_mul_f32_e64 v15, v128, v15
	v_mul_f32_e64 v12, v128, v12
	v_mul_f32_e64 v13, v128, v13
	v_pk_mul_f32 v[10:11], v[128:129], v[10:11] op_sel_hi:[0,1]
	v_pk_mul_f32 v[8:9], v[128:129], v[8:9] op_sel_hi:[0,1]
	v_pk_mul_f32 v[6:7], v[128:129], v[6:7] op_sel_hi:[0,1]
	v_pk_mul_f32 v[4:5], v[128:129], v[4:5] op_sel_hi:[0,1]
	s_waitcnt vmcnt(1)
	v_mfma_f32_32x32x16_bf16 v[16:31], v[40:43], v[68:71], v[16:31]
	global_load_dwordx4 v[40:43], v[96:97], off offset:-4096
	v_mul_f32_e64 v2, v128, v2
	v_mul_f32_e64 v3, v128, v3
	v_mul_f32_e64 v0, v128, v0
	v_mul_f32_e64 v1, v128, v1
	s_waitcnt vmcnt(1)
	v_mfma_f32_32x32x16_bf16 v[16:31], v[32:35], v[64:67], v[16:31]
	s_nop 11
	v_pk_mul_f32 v[30:31], v[130:131], v[30:31] op_sel_hi:[0,1]
	v_pk_mul_f32 v[28:29], v[130:131], v[28:29] op_sel_hi:[0,1]
	v_pk_mul_f32 v[26:27], v[130:131], v[26:27] op_sel_hi:[0,1]
	v_pk_mul_f32 v[24:25], v[130:131], v[24:25] op_sel_hi:[0,1]
	v_pk_mul_f32 v[22:23], v[130:131], v[22:23] op_sel_hi:[0,1]
	v_pk_mul_f32 v[20:21], v[130:131], v[20:21] op_sel_hi:[0,1]
	v_pk_mul_f32 v[18:19], v[130:131], v[18:19] op_sel_hi:[0,1]
	v_pk_mul_f32 v[16:17], v[130:131], v[16:17] op_sel_hi:[0,1]
	s_waitcnt vmcnt(0)
	s_nop 0
	v_mfma_f32_32x32x16_bf16 v[16:31], v[40:43], v[92:95], v[16:31]
	v_mfma_f32_32x32x16_bf16 v[16:31], v[36:39], v[88:91], v[16:31]
	ds_read_b128 v[32:35], v121
	ds_read_b128 v[36:39], v121 offset:32
	s_waitcnt lgkmcnt(1)
	v_mfma_f32_32x32x16_bf16 v[0:15], v[152:155], v[32:35], v[0:15]
	global_load_dwordx4 v[32:35], v[62:63], off offset:2048
	s_waitcnt lgkmcnt(0)
	v_mfma_f32_32x32x16_bf16 v[0:15], v[156:159], v[36:39], v[0:15]
	global_load_dwordx4 v[36:39], v[62:63], off offset:3072
	ds_read_b128 v[40:43], v121 offset:64
	ds_read_b128 v[44:47], v121 offset:96
	v_lshl_add_u64 v[62:63], v[108:109], 0, s[8:9]
	s_mov_b32 s8, 0x9000
	s_waitcnt lgkmcnt(1)
	v_mfma_f32_32x32x16_bf16 v[0:15], v[160:163], v[40:43], v[0:15]
	global_load_dwordx4 v[40:43], v[96:97], off
	s_waitcnt lgkmcnt(0)
	v_mfma_f32_32x32x16_bf16 v[0:15], v[164:167], v[44:47], v[0:15]
	global_load_dwordx4 v[44:47], v[96:97], off offset:1024
	ds_read_b128 v[48:51], v121 offset:128
	ds_read_b128 v[52:55], v121 offset:160
	s_waitcnt lgkmcnt(1)
	v_mfma_f32_32x32x16_bf16 v[0:15], v[176:179], v[48:51], v[0:15]
	global_load_dwordx4 v[48:51], v[96:97], off offset:2048
	s_waitcnt lgkmcnt(0)
	v_mfma_f32_32x32x16_bf16 v[0:15], v[168:171], v[52:55], v[0:15]
	global_load_dwordx4 v[52:55], v[96:97], off offset:3072
	ds_read_b128 v[58:61], v121 offset:192
	ds_read_b128 v[96:99], v121 offset:224
	s_waitcnt lgkmcnt(1)
	v_mfma_f32_32x32x16_bf16 v[0:15], v[172:175], v[58:61], v[0:15]
	global_load_dwordx4 v[58:61], v[62:63], off
	s_waitcnt lgkmcnt(0)
	v_mfma_f32_32x32x16_bf16 v[0:15], v[192:195], v[96:99], v[0:15]
	s_waitcnt vmcnt(6)
	v_mfma_f32_32x32x16_bf16 v[16:31], v[32:35], v[84:87], v[16:31]
	global_load_dwordx4 v[32:35], v[62:63], off offset:1024
	s_nop 8
	v_mul_f32_e32 v182, v1, v1
	v_fmac_f32_e32 v182, v0, v0
	v_fmac_f32_e32 v182, v2, v2
	v_fmac_f32_e32 v182, v3, v3
	v_fmac_f32_e32 v182, v4, v4
	v_fmac_f32_e32 v182, v5, v5
	s_waitcnt vmcnt(6)
; #define LAS __attribute__((address_space(3)))
; #define MFMA32(a, b, c) __builtin_amdgcn_mfma_f32_32x32x16_bf16((a), (b), (c), 0, 0, 0)
; __device__ __forceinline__ void phase_ret_out(const Frame& F, const Args& a, int l) {
;     ...
;         for (int dt = 0; dt < 4; ++dt) {
;             const int dvr = 128 * dj + 32 * dt + li;
;             const bf16* srow = SB + (((size_t)((seq * 4 + h) * 32 + n) * 8 + 4 * dj + dt) * 2) * 8 * 512 + lane * 8;
;             const bf16* vrow = RVT + ((size_t)(h * 8 + 4 * dj + dt) * (T / 16) + (tok0 >> 4)) * 512 + lane * 8;
;             f32x16 acc;
; #pragma unroll
;             for (int e = 0; e < 16; ++e) acc[e] = 0.f;
;             bf16x8 s0f[8], s1f[8], vff[8];
; #pragma unroll
;             for (int ks = 0; ks < 8; ++ks) { s0f[ks] = *(const bf16x8*)(srow + 512 * ks); s1f[ks] = *(const bf16x8*)(srow + 4096 + 512 * ks); vff[ks] = *(const bf16x8*)(vrow + 512 * ks); }
;             asm volatile("" ::: "memory");
; #pragma unroll
;             for (int ks = 0; ks < 8; ++ks) acc = MFMA32(s0f[ks], qf[ks], acc);
; #pragma unroll
;             for (int e = 0; e < 16; ++e) acc[e] *= ratio;
; #pragma unroll
;             for (int ks = 0; ks < 8; ++ks) acc = MFMA32(s1f[ks], qf[ks], acc);
; #pragma unroll
;             for (int e = 0; e < 16; ++e) acc[e] *= xi1;
; #pragma unroll
;             for (int ks = 0; ks < 8; ++ks) { const bf16x8 pf = *(const LAS bf16x8*)(Pl + (qi * 32 + li) * PLD + (16 * ks + 8 * hh) * 2); acc = MFMA32(vff[ks], pf, acc); }
; #pragma unroll
;             for (int e = 0; e < 16; ++e) { s1 += acc[e]; s2 += acc[e] * acc[e]; }
	v_mfma_f32_32x32x16_bf16 v[16:31], v[36:39], v[80:83], v[16:31]
	global_load_dwordx4 v[36:39], v[62:63], off offset:2048
	v_fmac_f32_e32 v182, v6, v6
	v_fmac_f32_e32 v182, v7, v7
	v_fmac_f32_e32 v182, v8, v8
	v_fmac_f32_e32 v182, v9, v9
	v_fmac_f32_e32 v182, v10, v10
	v_fmac_f32_e32 v182, v11, v11
	s_waitcnt vmcnt(6)
	v_mfma_f32_32x32x16_bf16 v[16:31], v[40:43], v[76:79], v[16:31]
	global_load_dwordx4 v[40:43], v[62:63], off offset:3072
	v_add_co_u32_e32 v62, vcc, s33, v62
	v_fmac_f32_e32 v182, v12, v12
	s_nop 0
	v_addc_co_u32_e32 v63, vcc, 0, v63, vcc
	v_fmac_f32_e32 v182, v13, v13
	s_waitcnt vmcnt(6)
	v_mfma_f32_32x32x16_bf16 v[16:31], v[44:47], v[72:75], v[16:31]
	global_load_dwordx4 v[44:47], v[62:63], off
	v_fmac_f32_e32 v182, v14, v14
	v_fmac_f32_e32 v182, v15, v15
	s_waitcnt vmcnt(6)
	v_mfma_f32_32x32x16_bf16 v[16:31], v[48:51], v[68:71], v[16:31]
	global_load_dwordx4 v[96:99], v[62:63], off offset:1024
	global_load_dwordx4 v[100:103], v[62:63], off offset:2048
	global_load_dwordx4 v[48:51], v[62:63], off offset:3072
	v_add_co_u32_e32 v62, vcc, s8, v56
	ds_read_b128 v[132:135], v121 offset:32
	s_nop 0
	v_addc_co_u32_e32 v63, vcc, 0, v57, vcc
	s_waitcnt vmcnt(8)
	v_mfma_f32_32x32x16_bf16 v[16:31], v[52:55], v[64:67], v[16:31]
	ds_read_b128 v[52:55], v121
	s_mov_b32 s8, 0x8000
	v_add_co_u32_e32 v140, vcc, s8, v56
	s_mov_b32 s8, 0xb000
	s_nop 0
	v_addc_co_u32_e32 v141, vcc, 0, v57, vcc
	s_nop 5
	v_pk_mul_f32 v[30:31], v[128:129], v[30:31] op_sel_hi:[0,1]
	v_pk_mul_f32 v[28:29], v[128:129], v[28:29] op_sel_hi:[0,1]
	v_pk_mul_f32 v[26:27], v[128:129], v[26:27] op_sel_hi:[0,1]
	v_pk_mul_f32 v[24:25], v[128:129], v[24:25] op_sel_hi:[0,1]
	v_pk_mul_f32 v[22:23], v[128:129], v[22:23] op_sel_hi:[0,1]
	v_pk_mul_f32 v[20:21], v[128:129], v[20:21] op_sel_hi:[0,1]
	v_pk_mul_f32 v[18:19], v[128:129], v[18:19] op_sel_hi:[0,1]
	v_pk_mul_f32 v[16:17], v[128:129], v[16:17] op_sel_hi:[0,1]
	s_waitcnt vmcnt(7) lgkmcnt(0)
	s_nop 0
	v_mfma_f32_32x32x16_bf16 v[16:31], v[58:61], v[52:55], v[16:31]
	global_load_dwordx4 v[58:61], v[62:63], off offset:-4096
	s_waitcnt vmcnt(7)
	v_mfma_f32_32x32x16_bf16 v[16:31], v[32:35], v[132:135], v[16:31]
	global_load_dwordx4 v[132:135], v[140:141], off offset:1024
	ds_read_b128 v[32:35], v121 offset:64
	ds_read_b128 v[52:55], v121 offset:96
	global_load_dwordx4 v[136:139], v[140:141], off offset:2048
	s_nop 0
	global_load_dwordx4 v[140:143], v[140:141], off offset:3072
	s_waitcnt vmcnt(9) lgkmcnt(1)
	v_mfma_f32_32x32x16_bf16 v[16:31], v[36:39], v[32:35], v[16:31]
	ds_read_b128 v[32:35], v121 offset:128
	ds_read_b128 v[36:39], v121 offset:160
	global_load_dwordx4 v[144:147], v[62:63], off
	s_waitcnt vmcnt(9) lgkmcnt(2)
	v_mfma_f32_32x32x16_bf16 v[16:31], v[40:43], v[52:55], v[16:31]
	s_waitcnt vmcnt(8) lgkmcnt(1)
	v_mfma_f32_32x32x16_bf16 v[16:31], v[44:47], v[32:35], v[16:31]
	s_waitcnt vmcnt(7) lgkmcnt(0)
	v_mfma_f32_32x32x16_bf16 v[16:31], v[96:99], v[36:39], v[16:31]
	global_load_dwordx4 v[96:99], v[62:63], off offset:1024
	ds_read_b128 v[32:35], v121 offset:192
	ds_read_b128 v[52:55], v121 offset:224
	s_waitcnt vmcnt(7) lgkmcnt(1)
	v_mfma_f32_32x32x16_bf16 v[16:31], v[100:103], v[32:35], v[16:31]
	global_load_dwordx4 v[100:103], v[62:63], off offset:2048
	s_waitcnt vmcnt(6)
	v_mfma_f32_32x32x16_bf16 v[32:47], v[58:61], v[92:95], 0
	global_load_dwordx4 v[58:61], v[62:63], off offset:3072
	v_add_co_u32_e32 v62, vcc, s8, v56
	s_mov_b32 s8, 0xa000
	s_nop 0
	v_addc_co_u32_e32 v63, vcc, 0, v57, vcc
	v_add_co_u32_e32 v148, vcc, s8, v56
	s_waitcnt vmcnt(6)
	v_mfma_f32_32x32x16_bf16 v[32:47], v[132:135], v[88:91], v[32:47]
	global_load_dwordx4 v[132:135], v[62:63], off offset:-4096
	v_addc_co_u32_e32 v149, vcc, 0, v57, vcc
	s_or_b32 s8, s26, 2
	s_mul_hi_i32 s9, s8, 0xa00
	s_mulk_i32 s8, 0xa00
	s_add_u32 s8, s8, s6
	s_waitcnt vmcnt(6)
	v_mfma_f32_32x32x16_bf16 v[32:47], v[136:139], v[84:87], v[32:47]
	global_load_dwordx4 v[136:139], v[148:149], off offset:1024
	s_addc_u32 s9, s9, s7
	s_lshl_b64 s[8:9], s[8:9], 10
	s_waitcnt vmcnt(6)
	v_mfma_f32_32x32x16_bf16 v[32:47], v[140:143], v[80:83], v[32:47]
	global_load_dwordx4 v[140:143], v[148:149], off offset:2048
	s_waitcnt vmcnt(6)
	v_mfma_f32_32x32x16_bf16 v[32:47], v[144:147], v[76:79], v[32:47]
	global_load_dwordx4 v[144:147], v[148:149], off offset:3072
	s_waitcnt vmcnt(6)
	v_mfma_f32_32x32x16_bf16 v[32:47], v[96:99], v[72:75], v[32:47]
	global_load_dwordx4 v[96:99], v[62:63], off
	s_waitcnt vmcnt(6)
	v_mfma_f32_32x32x16_bf16 v[32:47], v[100:103], v[68:71], v[32:47]
	global_load_dwordx4 v[100:103], v[62:63], off offset:1024
	global_load_dwordx4 v[148:151], v[62:63], off offset:2048
	global_load_dwordx4 v[152:155], v[62:63], off offset:3072
	v_lshl_add_u64 v[62:63], v[108:109], 0, s[8:9]
	s_mov_b32 s8, 0xd000
	s_waitcnt vmcnt(8)
	v_mfma_f32_32x32x16_bf16 v[32:47], v[58:61], v[64:67], v[32:47]
	global_load_dwordx4 v[58:61], v[62:63], off
	s_nop 10
	v_pk_mul_f32 v[46:47], v[130:131], v[46:47] op_sel_hi:[0,1]
	v_pk_mul_f32 v[44:45], v[130:131], v[44:45] op_sel_hi:[0,1]
	v_pk_mul_f32 v[42:43], v[130:131], v[42:43] op_sel_hi:[0,1]
	v_pk_mul_f32 v[40:41], v[130:131], v[40:41] op_sel_hi:[0,1]
	v_pk_mul_f32 v[38:39], v[130:131], v[38:39] op_sel_hi:[0,1]
	v_pk_mul_f32 v[36:37], v[130:131], v[36:37] op_sel_hi:[0,1]
	v_pk_mul_f32 v[34:35], v[130:131], v[34:35] op_sel_hi:[0,1]
	v_pk_mul_f32 v[32:33], v[130:131], v[32:33] op_sel_hi:[0,1]
	s_waitcnt lgkmcnt(0)
	v_mfma_f32_32x32x16_bf16 v[16:31], v[48:51], v[52:55], v[16:31]
	v_add_f32_e32 v131, 0, v0
	v_add_f32_e32 v131, v1, v131
	v_add_f32_e32 v131, v2, v131
	v_add_f32_e32 v131, v3, v131
	v_add_f32_e32 v131, v4, v131
	v_add_f32_e32 v131, v5, v131
	s_nop 5
	v_fmac_f32_e32 v182, v16, v16
	s_waitcnt vmcnt(8)
; #define LAS __attribute__((address_space(3)))
; #define MFMA32(a, b, c) __builtin_amdgcn_mfma_f32_32x32x16_bf16((a), (b), (c), 0, 0, 0)
; __device__ __forceinline__ void phase_ret_out(const Frame& F, const Args& a, int l) {
;     ...
;         for (int dt = 0; dt < 4; ++dt) {
;             const int dvr = 128 * dj + 32 * dt + li;
;             const bf16* srow = SB + (((size_t)((seq * 4 + h) * 32 + n) * 8 + 4 * dj + dt) * 2) * 8 * 512 + lane * 8;
;             const bf16* vrow = RVT + ((size_t)(h * 8 + 4 * dj + dt) * (T / 16) + (tok0 >> 4)) * 512 + lane * 8;
;             f32x16 acc;
; #pragma unroll
;             for (int e = 0; e < 16; ++e) acc[e] = 0.f;
;             bf16x8 s0f[8], s1f[8], vff[8];
; #pragma unroll
;             for (int ks = 0; ks < 8; ++ks) { s0f[ks] = *(const bf16x8*)(srow + 512 * ks); s1f[ks] = *(const bf16x8*)(srow + 4096 + 512 * ks); vff[ks] = *(const bf16x8*)(vrow + 512 * ks); }
;             asm volatile("" ::: "memory");
; #pragma unroll
;             for (int ks = 0; ks < 8; ++ks) acc = MFMA32(s0f[ks], qf[ks], acc);
; #pragma unroll
;             for (int e = 0; e < 16; ++e) acc[e] *= ratio;
; #pragma unroll
;             for (int ks = 0; ks < 8; ++ks) acc = MFMA32(s1f[ks], qf[ks], acc);
; #pragma unroll
;             for (int e = 0; e < 16; ++e) acc[e] *= xi1;
; #pragma unroll
;             for (int ks = 0; ks < 8; ++ks) { const bf16x8 pf = *(const LAS bf16x8*)(Pl + (qi * 32 + li) * PLD + (16 * ks + 8 * hh) * 2); acc = MFMA32(vff[ks], pf, acc); }
; #pragma unroll
;             for (int e = 0; e < 16; ++e) { s1 += acc[e]; s2 += acc[e] * acc[e]; }
	v_mfma_f32_32x32x16_bf16 v[32:47], v[132:135], v[92:95], v[32:47]
	global_load_dwordx4 v[132:135], v[62:63], off offset:1024
	v_fmac_f32_e32 v182, v17, v17
	v_fmac_f32_e32 v182, v18, v18
	v_fmac_f32_e32 v182, v19, v19
	v_fmac_f32_e32 v182, v20, v20
	v_fmac_f32_e32 v182, v21, v21
	v_fmac_f32_e32 v182, v22, v22
	s_waitcnt vmcnt(8)
	v_mfma_f32_32x32x16_bf16 v[32:47], v[136:139], v[88:91], v[32:47]
	global_load_dwordx4 v[136:139], v[62:63], off offset:2048
	v_fmac_f32_e32 v182, v23, v23
	v_fmac_f32_e32 v182, v24, v24
	v_fmac_f32_e32 v182, v25, v25
	v_fmac_f32_e32 v182, v26, v26
	v_fmac_f32_e32 v182, v27, v27
	v_fmac_f32_e32 v182, v28, v28
	s_waitcnt vmcnt(8)
	v_mfma_f32_32x32x16_bf16 v[32:47], v[140:143], v[84:87], v[32:47]
	global_load_dwordx4 v[140:143], v[62:63], off offset:3072
	v_add_co_u32_e32 v62, vcc, s33, v62
	v_fmac_f32_e32 v182, v29, v29
	s_nop 0
	v_addc_co_u32_e32 v63, vcc, 0, v63, vcc
	v_fmac_f32_e32 v182, v30, v30
	s_waitcnt vmcnt(8)
	v_mfma_f32_32x32x16_bf16 v[32:47], v[144:147], v[80:83], v[32:47]
	v_fmac_f32_e32 v182, v31, v31
	s_waitcnt vmcnt(7)
	v_mfma_f32_32x32x16_bf16 v[32:47], v[96:99], v[76:79], v[32:47]
	s_waitcnt vmcnt(6)
	v_mfma_f32_32x32x16_bf16 v[32:47], v[100:103], v[72:75], v[32:47]
	global_load_dwordx4 v[144:147], v[62:63], off
	global_load_dwordx4 v[156:159], v[62:63], off offset:1024
	global_load_dwordx4 v[100:103], v[62:63], off offset:2048
	global_load_dwordx4 v[96:99], v[62:63], off offset:3072
	v_add_co_u32_e32 v62, vcc, s8, v56
	s_mov_b32 s8, 0xc000
	s_nop 0
	v_addc_co_u32_e32 v63, vcc, 0, v57, vcc
	s_waitcnt vmcnt(9)
	v_mfma_f32_32x32x16_bf16 v[32:47], v[148:151], v[68:71], v[32:47]
	global_load_dwordx4 v[148:151], v[62:63], off offset:-4096
	v_add_co_u32_e32 v164, vcc, s8, v56
	ds_read_b128 v[48:51], v121
	ds_read_b128 v[52:55], v121 offset:32
	v_addc_co_u32_e32 v165, vcc, 0, v57, vcc
	s_waitcnt vmcnt(9)
	v_mfma_f32_32x32x16_bf16 v[32:47], v[152:155], v[64:67], v[32:47]
	global_load_dwordx4 v[152:155], v[164:165], off offset:1024
	global_load_dwordx4 v[160:163], v[164:165], off offset:2048
	s_mov_b32 s8, 0xf000
	global_load_dwordx4 v[164:167], v[164:165], off offset:3072
	v_add_co_u32_e32 v172, vcc, s8, v56
	s_mov_b32 s8, 0xe000
	s_nop 5
	v_pk_mul_f32 v[46:47], v[128:129], v[46:47] op_sel_hi:[0,1]
	v_pk_mul_f32 v[44:45], v[128:129], v[44:45] op_sel_hi:[0,1]
	v_pk_mul_f32 v[42:43], v[128:129], v[42:43] op_sel_hi:[0,1]
	v_pk_mul_f32 v[40:41], v[128:129], v[40:41] op_sel_hi:[0,1]
	v_pk_mul_f32 v[38:39], v[128:129], v[38:39] op_sel_hi:[0,1]
	v_pk_mul_f32 v[36:37], v[128:129], v[36:37] op_sel_hi:[0,1]
	v_pk_mul_f32 v[34:35], v[128:129], v[34:35] op_sel_hi:[0,1]
	v_pk_mul_f32 v[32:33], v[128:129], v[32:33] op_sel_hi:[0,1]
	v_addc_co_u32_e32 v173, vcc, 0, v57, vcc
	s_waitcnt vmcnt(11) lgkmcnt(1)
	v_mfma_f32_32x32x16_bf16 v[32:47], v[58:61], v[48:51], v[32:47]
	v_add_co_u32_e32 v168, vcc, s8, v56
	s_or_b32 s8, s26, 3
	s_nop 0
	v_addc_co_u32_e32 v169, vcc, 0, v57, vcc
	s_mul_hi_i32 s9, s8, 0xa00
	s_mulk_i32 s8, 0xa00
	s_waitcnt vmcnt(10) lgkmcnt(0)
	v_mfma_f32_32x32x16_bf16 v[32:47], v[132:135], v[52:55], v[32:47]
	global_load_dwordx4 v[132:135], v[62:63], off
	ds_read_b128 v[48:51], v121 offset:64
	ds_read_b128 v[52:55], v121 offset:96
	s_add_u32 s6, s8, s6
	s_addc_u32 s7, s9, s7
	s_lshl_b64 s[6:7], s[6:7], 10
	v_lshl_add_u64 v[180:181], v[108:109], 0, s[6:7]
	s_waitcnt vmcnt(10) lgkmcnt(1)
	v_mfma_f32_32x32x16_bf16 v[32:47], v[136:139], v[48:51], v[32:47]
	global_load_dwordx4 v[136:139], v[62:63], off offset:1024
	s_waitcnt vmcnt(10) lgkmcnt(0)
	v_mfma_f32_32x32x16_bf16 v[32:47], v[140:143], v[52:55], v[32:47]
	global_load_dwordx4 v[140:143], v[62:63], off offset:2048
	ds_read_b128 v[48:51], v121 offset:128
	ds_read_b128 v[52:55], v121 offset:160
	s_waitcnt vmcnt(10) lgkmcnt(1)
	v_mfma_f32_32x32x16_bf16 v[32:47], v[144:147], v[48:51], v[32:47]
	global_load_dwordx4 v[144:147], v[62:63], off offset:3072
	s_waitcnt vmcnt(10) lgkmcnt(0)
	v_mfma_f32_32x32x16_bf16 v[32:47], v[156:159], v[52:55], v[32:47]
	global_load_dwordx4 v[156:159], v[172:173], off offset:-4096
	s_waitcnt vmcnt(8)
	v_mfma_f32_32x32x16_bf16 v[48:63], v[148:151], v[92:95], 0
	global_load_dwordx4 v[148:151], v[168:169], off offset:1024
	s_waitcnt vmcnt(8)
	v_mfma_f32_32x32x16_bf16 v[48:63], v[152:155], v[88:91], v[48:63]
	global_load_dwordx4 v[152:155], v[168:169], off offset:2048
	s_waitcnt vmcnt(8)
	v_mfma_f32_32x32x16_bf16 v[48:63], v[160:163], v[84:87], v[48:63]
	global_load_dwordx4 v[160:163], v[168:169], off offset:3072
	s_waitcnt vmcnt(8)
	v_mfma_f32_32x32x16_bf16 v[48:63], v[164:167], v[80:83], v[48:63]
	global_load_dwordx4 v[164:167], v[172:173], off
	global_load_dwordx4 v[168:171], v[172:173], off offset:2048
	s_waitcnt vmcnt(9)
	v_mfma_f32_32x32x16_bf16 v[48:63], v[132:135], v[76:79], v[48:63]
	global_load_dwordx4 v[132:135], v[172:173], off offset:1024
	s_waitcnt vmcnt(9)
	v_mfma_f32_32x32x16_bf16 v[48:63], v[136:139], v[72:75], v[48:63]
	global_load_dwordx4 v[136:139], v[172:173], off offset:3072
	s_waitcnt vmcnt(9)
	v_mfma_f32_32x32x16_bf16 v[48:63], v[140:143], v[68:71], v[48:63]
	ds_read_b128 v[140:143], v121 offset:192
	ds_read_b128 v[172:175], v121 offset:224
	s_waitcnt vmcnt(8)
	v_mfma_f32_32x32x16_bf16 v[48:63], v[144:147], v[64:67], v[48:63]
	global_load_dwordx4 v[144:147], v[180:181], off
	global_load_dwordx4 v[176:179], v[180:181], off offset:1024
	s_nop 9
	v_pk_mul_f32 v[62:63], v[130:131], v[62:63] op_sel_hi:[0,1]
	v_pk_mul_f32 v[60:61], v[130:131], v[60:61] op_sel_hi:[0,1]
	v_pk_mul_f32 v[58:59], v[130:131], v[58:59] op_sel_hi:[0,1]
	v_pk_mul_f32 v[56:57], v[130:131], v[56:57] op_sel_hi:[0,1]
	v_pk_mul_f32 v[54:55], v[130:131], v[54:55] op_sel_hi:[0,1]
	v_pk_mul_f32 v[52:53], v[130:131], v[52:53] op_sel_hi:[0,1]
	v_pk_mul_f32 v[50:51], v[130:131], v[50:51] op_sel_hi:[0,1]
	v_pk_mul_f32 v[48:49], v[130:131], v[48:49] op_sel_hi:[0,1]
	s_waitcnt lgkmcnt(1)
; #define LAS __attribute__((address_space(3)))
; __device__ __forceinline__ float shfl_xor_(float v, int m) { return __builtin_bit_cast(float, __builtin_amdgcn_ds_bpermute((lane_id() ^ m) << 2, __builtin_bit_cast(int, v))); }
; #define MFMA32(a, b, c) __builtin_amdgcn_mfma_f32_32x32x16_bf16((a), (b), (c), 0, 0, 0)
; __device__ __forceinline__ void phase_ret_out(const Frame& F, const Args& a, int l) {
;     ...
;             for (int ks = 0; ks < 8; ++ks) acc = MFMA32(s0f[ks], qf[ks], acc);
; #pragma unroll
;             for (int e = 0; e < 16; ++e) acc[e] *= ratio;
; #pragma unroll
;             for (int ks = 0; ks < 8; ++ks) acc = MFMA32(s1f[ks], qf[ks], acc);
; #pragma unroll
;             for (int e = 0; e < 16; ++e) acc[e] *= xi1;
; #pragma unroll
;             for (int ks = 0; ks < 8; ++ks) { const bf16x8 pf = *(const LAS bf16x8*)(Pl + (qi * 32 + li) * PLD + (16 * ks + 8 * hh) * 2); acc = MFMA32(vff[ks], pf, acc); }
; #pragma unroll
;             for (int e = 0; e < 16; ++e) { s1 += acc[e]; s2 += acc[e] * acc[e]; }
;             o[dt] = acc;
;         }
;         s1 += shfl_xor_(s1, 32); s2 += shfl_xor_(s2, 32);
;         if (hh == 0) SX[(dj * 4 + qi) * 32 + li] = (f32x2){s1, s2};
	v_mfma_f32_32x32x16_bf16 v[32:47], v[100:103], v[140:143], v[32:47]
	s_waitcnt vmcnt(9)
	v_mfma_f32_32x32x16_bf16 v[48:63], v[156:159], v[92:95], v[48:63]
	v_add_f32_e32 v92, v6, v131
	v_add_f32_e32 v92, v7, v92
	v_add_f32_e32 v100, v8, v92
	global_load_dwordx4 v[92:95], v[180:181], off offset:2048
	s_waitcnt vmcnt(9)
	v_mfma_f32_32x32x16_bf16 v[48:63], v[148:151], v[88:91], v[48:63]
	v_add_f32_e32 v88, v9, v100
	v_add_f32_e32 v88, v10, v88
	v_add_f32_e32 v100, v11, v88
	global_load_dwordx4 v[88:91], v[180:181], off offset:3072
	v_add_f32_e32 v102, v12, v100
	v_add_co_u32_e32 v100, vcc, s33, v180
	s_waitcnt vmcnt(9)
	v_mfma_f32_32x32x16_bf16 v[48:63], v[152:155], v[84:87], v[48:63]
	v_addc_co_u32_e32 v101, vcc, 0, v181, vcc
	global_load_dwordx4 v[84:87], v[100:101], off
	s_waitcnt vmcnt(9)
	v_mfma_f32_32x32x16_bf16 v[48:63], v[160:163], v[80:83], v[48:63]
	v_add_f32_e32 v80, v13, v102
	v_add_f32_e32 v80, v14, v80
	v_add_f32_e32 v102, v15, v80
	global_load_dwordx4 v[80:83], v[100:101], off offset:1024
	s_waitcnt vmcnt(9)
	v_mfma_f32_32x32x16_bf16 v[48:63], v[164:167], v[76:79], v[48:63]
	v_add_f32_e32 v76, v102, v16
	v_add_f32_e32 v76, v17, v76
	v_add_f32_e32 v102, v18, v76
	global_load_dwordx4 v[76:79], v[100:101], off offset:2048
	s_waitcnt vmcnt(8)
	v_mfma_f32_32x32x16_bf16 v[48:63], v[132:135], v[72:75], v[48:63]
	v_add_f32_e32 v72, v19, v102
	v_add_f32_e32 v72, v20, v72
	v_add_f32_e32 v102, v21, v72
	global_load_dwordx4 v[72:75], v[100:101], off offset:3072
	v_mfma_f32_32x32x16_bf16 v[48:63], v[168:171], v[68:71], v[48:63]
	v_add_f32_e32 v68, v22, v102
	v_add_f32_e32 v68, v23, v68
	v_add_f32_e32 v68, v24, v68
	s_waitcnt vmcnt(8)
	v_mfma_f32_32x32x16_bf16 v[48:63], v[136:139], v[64:67], v[48:63]
	v_add_f32_e32 v64, v25, v68
	v_add_f32_e32 v100, v26, v64
	ds_read_b128 v[64:67], v121
	ds_read_b128 v[68:71], v121 offset:32
	s_waitcnt lgkmcnt(2)
	v_mfma_f32_32x32x16_bf16 v[32:47], v[96:99], v[172:175], v[32:47]
	s_nop 5
	v_mul_f32_e64 v62, v128, v62
	v_mul_f32_e64 v63, v128, v63
	v_mul_f32_e64 v60, v128, v60
	v_mul_f32_e64 v61, v128, v61
	v_mul_f32_e64 v58, v128, v58
	v_mul_f32_e64 v59, v128, v59
	v_pk_mul_f32 v[56:57], v[128:129], v[56:57] op_sel_hi:[0,1]
	v_pk_mul_f32 v[54:55], v[128:129], v[54:55] op_sel_hi:[0,1]
	v_pk_mul_f32 v[52:53], v[128:129], v[52:53] op_sel_hi:[0,1]
	v_pk_mul_f32 v[50:51], v[128:129], v[50:51] op_sel_hi:[0,1]
	v_pk_mul_f32 v[48:49], v[128:129], v[48:49] op_sel_hi:[0,1]
	v_fmac_f32_e32 v182, v32, v32
	v_fmac_f32_e32 v182, v33, v33
	s_waitcnt vmcnt(7) lgkmcnt(1)
	v_mfma_f32_32x32x16_bf16 v[48:63], v[144:147], v[64:67], v[48:63]
	v_add_f32_e32 v64, v27, v100
	v_add_f32_e32 v64, v28, v64
	v_add_f32_e32 v64, v29, v64
	v_fmac_f32_e32 v182, v34, v34
	v_fmac_f32_e32 v182, v35, v35
	v_fmac_f32_e32 v182, v36, v36
	v_fmac_f32_e32 v182, v37, v37
	s_waitcnt vmcnt(6) lgkmcnt(0)
	v_mfma_f32_32x32x16_bf16 v[48:63], v[176:179], v[68:71], v[48:63]
	v_add_f32_e32 v68, v30, v64
	ds_read_b128 v[64:67], v121 offset:64
	v_add_f32_e32 v68, v31, v68
	v_add_f32_e32 v96, v68, v32
	ds_read_b128 v[68:71], v121 offset:96
	v_fmac_f32_e32 v182, v38, v38
	v_fmac_f32_e32 v182, v39, v39
	s_waitcnt vmcnt(5) lgkmcnt(1)
	v_mfma_f32_32x32x16_bf16 v[48:63], v[92:95], v[64:67], v[48:63]
	v_add_f32_e32 v64, v33, v96
	v_add_f32_e32 v64, v34, v64
	v_add_f32_e32 v64, v35, v64
	v_fmac_f32_e32 v182, v40, v40
	v_fmac_f32_e32 v182, v41, v41
	v_fmac_f32_e32 v182, v42, v42
	v_fmac_f32_e32 v182, v43, v43
	s_waitcnt vmcnt(4) lgkmcnt(0)
	v_mfma_f32_32x32x16_bf16 v[48:63], v[88:91], v[68:71], v[48:63]
	v_add_f32_e32 v68, v36, v64
	ds_read_b128 v[64:67], v121 offset:128
	v_add_f32_e32 v68, v37, v68
	v_add_f32_e32 v88, v38, v68
	ds_read_b128 v[68:71], v121 offset:160
	v_fmac_f32_e32 v182, v44, v44
	v_fmac_f32_e32 v182, v45, v45
	s_waitcnt vmcnt(3) lgkmcnt(1)
	v_mfma_f32_32x32x16_bf16 v[48:63], v[84:87], v[64:67], v[48:63]
	v_add_f32_e32 v64, v39, v88
	v_add_f32_e32 v64, v40, v64
	v_add_f32_e32 v64, v41, v64
	v_fmac_f32_e32 v182, v46, v46
	v_fmac_f32_e32 v182, v47, v47
	s_waitcnt vmcnt(2) lgkmcnt(0)
	v_mfma_f32_32x32x16_bf16 v[48:63], v[80:83], v[68:71], v[48:63]
	v_add_f32_e32 v68, v42, v64
	ds_read_b128 v[64:67], v121 offset:192
	v_add_f32_e32 v68, v43, v68
	v_add_f32_e32 v80, v44, v68
	ds_read_b128 v[68:71], v121 offset:224
	s_waitcnt vmcnt(1) lgkmcnt(1)
	v_mfma_f32_32x32x16_bf16 v[48:63], v[76:79], v[64:67], v[48:63]
	v_add_f32_e32 v64, v45, v80
	v_add_f32_e32 v64, v46, v64
	v_add_f32_e32 v64, v47, v64
	s_waitcnt vmcnt(0) lgkmcnt(0)
	v_mfma_f32_32x32x16_bf16 v[48:63], v[72:75], v[68:71], v[48:63]
	s_nop 11
	v_add_f32_e32 v64, v64, v48
	v_add_f32_e32 v64, v49, v64
	v_fmac_f32_e32 v182, v48, v48
	v_add_f32_e32 v64, v50, v64
	v_fmac_f32_e32 v182, v49, v49
	v_add_f32_e32 v64, v51, v64
	v_fmac_f32_e32 v182, v50, v50
	v_add_f32_e32 v78, v52, v64
	v_pk_mul_f32 v[64:65], v[62:63], v[62:63]
	v_pk_mul_f32 v[76:77], v[50:51], v[50:51]
	v_pk_mul_f32 v[74:75], v[52:53], v[52:53]
	v_add_f32_e32 v65, v77, v182
	v_add_f32_e32 v65, v74, v65
	v_pk_mul_f32 v[72:73], v[54:55], v[54:55]
	v_add_f32_e32 v65, v75, v65
	v_add_f32_e32 v65, v72, v65
	v_pk_mul_f32 v[70:71], v[56:57], v[56:57]
	v_add_f32_e32 v65, v73, v65
	v_add_f32_e32 v74, v53, v78
	v_add_f32_e32 v65, v70, v65
	v_pk_mul_f32 v[68:69], v[58:59], v[58:59]
	v_add_f32_e32 v74, v54, v74
	v_add_f32_e32 v65, v71, v65
	v_add_f32_e32 v72, v55, v74
	v_add_f32_e32 v65, v68, v65
	v_pk_mul_f32 v[66:67], v[60:61], v[60:61]
	v_add_f32_e32 v72, v56, v72
	v_add_f32_e32 v65, v69, v65
	v_add_f32_e32 v70, v57, v72
	v_add_f32_e32 v65, v66, v65
	v_add_f32_e32 v70, v58, v70
	v_add_f32_e32 v65, v67, v65
	v_add_f32_e32 v68, v59, v70
	v_add_f32_e32 v65, v64, v65
	v_mbcnt_lo_u32_b32 v64, -1, 0
	v_mbcnt_hi_u32_b32 v64, -1, v64
	v_add_f32_e32 v68, v60, v68
	v_lshlrev_b32_e32 v64, 2, v64
	v_add_f32_e32 v66, v61, v68
	v_xor_b32_e32 v68, 0x80, v64
	v_mbcnt_lo_u32_b32 v64, -1, 0
	v_mbcnt_hi_u32_b32 v64, -1, v64
	v_add_f32_e32 v66, v62, v66
	v_lshlrev_b32_e32 v64, 2, v64
	v_mul_f32_e32 v67, v63, v63
	v_xor_b32_e32 v69, 0x80, v64
	v_mov_b32_e32 v64, v63
	v_pk_add_f32 v[64:65], v[64:65], v[66:67]
	ds_bpermute_b32 v66, v68, v64
	ds_bpermute_b32 v67, v69, v65
	s_waitcnt lgkmcnt(0)
	v_pk_add_f32 v[64:65], v[64:65], v[66:67]
	s_and_saveexec_b64 s[6:7], s[4:5]
	s_cbranch_execz .LBB0_1205
	ds_write_b64 v123, v[64:65] offset:34816
	s_branch .LBB0_1205
